# strategy 4 whole-kernel form, younger half: static s_setprio 1 for waves 4-7 at entry, every GEMM per-phase flip deleted
# speedup vs baseline: 1.0018x; 1.0018x over previous
; #define LAS __attribute__((address_space(3)))
; __global__ void __launch_bounds__(512, 2) fwd(Args a) {
;     extern __shared__ __attribute__((aligned(16))) unsigned char lds_raw[];
;     LAS unsigned char* lds = (LAS unsigned char*)lds_raw;
;     const int G = gridDim.x, NGW = G * 8;
;     ...
;     unsigned char* ws = a.ws;
;     u64* ss = (u64*)(ws + WS_SS);
;     bf16_t* hb = (bf16_t*)(ws + WS_HB); bf16_t* ob = (bf16_t*)(ws + WS_OB); bf16_t* act = (bf16_t*)(ws + WS_R1); bf16_t* qkv = (bf16_t*)(ws + WS_R1);
;     const int lo = a.ph_lo, hi = a.ph_hi;
;     ...
;     volatile LAS unsigned* bst = (volatile LAS unsigned*)(lds + LDS_BYTES - 64);
;     if (threadIdx.x < 2) bst[threadIdx.x] = 0u;
;     XcdBarrier xbar; xbar.bar = (unsigned*)(ws + WS_BAR); xbar.x = 0; xbar.st = bst;
_Z3fwd4Args:
	s_load_dwordx16 s[36:51], s[0:1], 0x0
	s_load_dwordx16 s[4:19], s[0:1], 0x40
	v_and_b32_e32 v236, 0x3ff, v0
	s_mov_b32 s60, s2
	v_cmp_gt_u32_e32 vcc, 2, v236
	s_waitcnt lgkmcnt(0)
	v_readfirstlane_b32 s100, v236
	s_lshr_b32 s100, s100, 6
	s_cmp_ge_u32 s100, 4
	s_cbranch_scc0 .Lglob_prio_skip
	s_setprio 1
